# P0 p0_h3: filt_w2/filt_w3 columns kept in VGPRs per wave, layer-2/3 matvec loops as readlane+fmac (no per-position weight reloads); plus p0_mod de-serialisation; guarded final
# speedup vs baseline: 1.0193x; 1.0083x over previous
; __device__ __forceinline__ void p0_h3(const Args& a, int gw, int NGW, int lane) {
;     ...
;     const float fr = a.in[I_FFREQ][lane];
;     const float b1 = a.in[I_FB1][lane], b2 = a.in[I_FB2][lane], b3 = a.in[I_FB3][lane];
;     for (int p = gw; p < LP + LS; p += NGW) {
;     ...
;         for (int i = 0; i < 64; ++i) acc += __shfl(h, i) * a.in[I_FW2][i * 64 + lane];
;         h = sinf(fr * acc);
;         acc = b3;
;         for (int i = 0; i < 64; ++i) acc += __shfl(h, i) * a.in[I_FW3][i * 64 + lane];
.LBB0_54:
	s_cmpk_gt_i32 s40, 0x2fff
	s_cbranch_scc1 .LBB0_93
	s_waitcnt lgkmcnt(0)
	global_load_dword v1, v2, s[52:53]
	global_load_dword v14, v2, s[14:15]
	global_load_dword v15, v2, s[18:19]
	global_load_dword v16, v2, s[26:27]
	v_mov_b32_e32 v3, 0
	v_lshl_add_u64 v[6:7], s[50:51], 0, v[2:3]
	v_add_u32_e32 v2, -1, v4
	v_and_b32_e32 v2, 15, v2
	v_cvt_f32_ubyte0_e32 v2, v2
	v_mov_b32_e32 v17, 0x38d1b717
	v_fmac_f32_e32 v17, 0x3f7fff90, v2
	v_mbcnt_lo_u32_b32 v2, -1, 0
	s_mov_b64 s[0:1], 0x100000
	v_mbcnt_hi_u32_b32 v8, -1, v2
	v_and_b32_e32 v2, 0xfc, v5
	v_lshl_add_u64 v[6:7], v[6:7], 0, s[0:1]
	v_lshl_add_u64 v[4:5], s[12:13], 0, v[2:3]
	s_mov_b64 s[0:1], 0xa00
	v_lshlrev_b32_e32 v8, 2, v8
	v_or_b32_e32 v2, 0x700, v2
	v_cmp_ne_u32_e64 s[6:7], 0, v39
	v_cmp_gt_u32_e64 s[8:9], 33, v39
	v_cmp_lt_u32_e64 s[10:11], 16, v39
	v_lshl_add_u64 v[4:5], v[4:5], 0, s[0:1]
	v_and_b32_e32 v18, 0x100, v8
	v_lshl_add_u64 v[8:9], s[16:17], 0, v[2:3]
	v_lshl_add_u64 v[10:11], s[24:25], 0, v[2:3]
	s_movk_i32 s26, 0x1000
	s_brev_b32 s27, 18
	s_mov_b32 s28, 0xfe5163ab
	s_mov_b32 s29, 0x3c439041
	s_mov_b32 s30, 0xdb629599
	s_mov_b32 s31, 0xf534ddc0
	s_mov_b32 s33, 0xfc2757d1
	s_mov_b32 s34, 0x4e441529
	s_mov_b32 s35, 0xa2f9836e
	s_mov_b32 s36, 0x3fc90fda
	s_mov_b32 s37, 0x3f22f983
	s_mov_b32 s38, 0xbfc90fda
	v_mov_b32_e32 v19, 0x3c0881c4
	v_mov_b32_e32 v20, 0xbab64f3b
	s_brev_b32 s39, 1
	s_movk_i32 s42, 0x1f8
	s_mov_b64 s[0:1], 0xb00
	s_mov_b64 s[4:5], 0x800
	v_not_b32_e32 v21, 63
	v_not_b32_e32 v22, 31
	v_mov_b32_e32 v23, 0xffc00000
	v_mov_b32_e32 v24, 0x7fc00000
	v_mov_b64_e32 v[230:231], v[8:9]
	global_load_dword v102, v[230:231], off offset:-1792
	global_load_dword v103, v[230:231], off offset:-1536
	global_load_dword v104, v[230:231], off offset:-1280
	global_load_dword v105, v[230:231], off offset:-1024
	global_load_dword v106, v[230:231], off offset:-768
	global_load_dword v107, v[230:231], off offset:-512
	global_load_dword v108, v[230:231], off offset:-256
	global_load_dword v109, v[230:231], off offset:0
	v_lshl_add_u64 v[230:231], v[230:231], 0, s[4:5]
	global_load_dword v110, v[230:231], off offset:-1792
	global_load_dword v111, v[230:231], off offset:-1536
	global_load_dword v112, v[230:231], off offset:-1280
	global_load_dword v113, v[230:231], off offset:-1024
	global_load_dword v114, v[230:231], off offset:-768
	global_load_dword v115, v[230:231], off offset:-512
	global_load_dword v116, v[230:231], off offset:-256
	global_load_dword v117, v[230:231], off offset:0
	v_lshl_add_u64 v[230:231], v[230:231], 0, s[4:5]
	global_load_dword v118, v[230:231], off offset:-1792
	global_load_dword v119, v[230:231], off offset:-1536
	global_load_dword v120, v[230:231], off offset:-1280
	global_load_dword v121, v[230:231], off offset:-1024
	global_load_dword v122, v[230:231], off offset:-768
	global_load_dword v123, v[230:231], off offset:-512
	global_load_dword v124, v[230:231], off offset:-256
	global_load_dword v125, v[230:231], off offset:0
	v_lshl_add_u64 v[230:231], v[230:231], 0, s[4:5]
	global_load_dword v126, v[230:231], off offset:-1792
	global_load_dword v127, v[230:231], off offset:-1536
	global_load_dword v128, v[230:231], off offset:-1280
	global_load_dword v129, v[230:231], off offset:-1024
	global_load_dword v130, v[230:231], off offset:-768
	global_load_dword v131, v[230:231], off offset:-512
	global_load_dword v132, v[230:231], off offset:-256
	global_load_dword v133, v[230:231], off offset:0
	v_lshl_add_u64 v[230:231], v[230:231], 0, s[4:5]
	global_load_dword v134, v[230:231], off offset:-1792
	global_load_dword v135, v[230:231], off offset:-1536
	global_load_dword v136, v[230:231], off offset:-1280
	global_load_dword v137, v[230:231], off offset:-1024
	global_load_dword v138, v[230:231], off offset:-768
	global_load_dword v139, v[230:231], off offset:-512
	global_load_dword v140, v[230:231], off offset:-256
	global_load_dword v141, v[230:231], off offset:0
	v_lshl_add_u64 v[230:231], v[230:231], 0, s[4:5]
	global_load_dword v142, v[230:231], off offset:-1792
	global_load_dword v143, v[230:231], off offset:-1536
	global_load_dword v144, v[230:231], off offset:-1280
	global_load_dword v145, v[230:231], off offset:-1024
	global_load_dword v146, v[230:231], off offset:-768
	global_load_dword v147, v[230:231], off offset:-512
	global_load_dword v148, v[230:231], off offset:-256
	global_load_dword v149, v[230:231], off offset:0
	v_lshl_add_u64 v[230:231], v[230:231], 0, s[4:5]
	global_load_dword v150, v[230:231], off offset:-1792
	global_load_dword v151, v[230:231], off offset:-1536
; __device__ __forceinline__ void p0_h3(const Args& a, int gw, int NGW, int lane) {
;     ...
;         for (int i = 0; i < 64; ++i) acc += __shfl(h, i) * a.in[I_FW2][i * 64 + lane];
;         h = sinf(fr * acc);
;         acc = b3;
;         for (int i = 0; i < 64; ++i) acc += __shfl(h, i) * a.in[I_FW3][i * 64 + lane];
	global_load_dword v152, v[230:231], off offset:-1280
	global_load_dword v153, v[230:231], off offset:-1024
	global_load_dword v154, v[230:231], off offset:-768
	global_load_dword v155, v[230:231], off offset:-512
	global_load_dword v156, v[230:231], off offset:-256
	global_load_dword v157, v[230:231], off offset:0
	v_lshl_add_u64 v[230:231], v[230:231], 0, s[4:5]
	global_load_dword v158, v[230:231], off offset:-1792
	global_load_dword v159, v[230:231], off offset:-1536
	global_load_dword v160, v[230:231], off offset:-1280
	global_load_dword v161, v[230:231], off offset:-1024
	global_load_dword v162, v[230:231], off offset:-768
	global_load_dword v163, v[230:231], off offset:-512
	global_load_dword v164, v[230:231], off offset:-256
	global_load_dword v165, v[230:231], off offset:0
	v_mov_b64_e32 v[230:231], v[10:11]
	global_load_dword v166, v[230:231], off offset:-1792
	global_load_dword v167, v[230:231], off offset:-1536
	global_load_dword v168, v[230:231], off offset:-1280
	global_load_dword v169, v[230:231], off offset:-1024
	global_load_dword v170, v[230:231], off offset:-768
	global_load_dword v171, v[230:231], off offset:-512
	global_load_dword v172, v[230:231], off offset:-256
	global_load_dword v173, v[230:231], off offset:0
	v_lshl_add_u64 v[230:231], v[230:231], 0, s[4:5]
	global_load_dword v174, v[230:231], off offset:-1792
	global_load_dword v175, v[230:231], off offset:-1536
	global_load_dword v176, v[230:231], off offset:-1280
	global_load_dword v177, v[230:231], off offset:-1024
	global_load_dword v178, v[230:231], off offset:-768
	global_load_dword v179, v[230:231], off offset:-512
	global_load_dword v180, v[230:231], off offset:-256
	global_load_dword v181, v[230:231], off offset:0
	v_lshl_add_u64 v[230:231], v[230:231], 0, s[4:5]
	global_load_dword v182, v[230:231], off offset:-1792
	global_load_dword v183, v[230:231], off offset:-1536
	global_load_dword v184, v[230:231], off offset:-1280
	global_load_dword v185, v[230:231], off offset:-1024
	global_load_dword v186, v[230:231], off offset:-768
	global_load_dword v187, v[230:231], off offset:-512
	global_load_dword v188, v[230:231], off offset:-256
	global_load_dword v189, v[230:231], off offset:0
	v_lshl_add_u64 v[230:231], v[230:231], 0, s[4:5]
	global_load_dword v190, v[230:231], off offset:-1792
	global_load_dword v191, v[230:231], off offset:-1536
	global_load_dword v192, v[230:231], off offset:-1280
	global_load_dword v193, v[230:231], off offset:-1024
	global_load_dword v194, v[230:231], off offset:-768
	global_load_dword v195, v[230:231], off offset:-512
	global_load_dword v196, v[230:231], off offset:-256
	global_load_dword v197, v[230:231], off offset:0
	v_lshl_add_u64 v[230:231], v[230:231], 0, s[4:5]
	global_load_dword v198, v[230:231], off offset:-1792
	global_load_dword v199, v[230:231], off offset:-1536
	global_load_dword v200, v[230:231], off offset:-1280
	global_load_dword v201, v[230:231], off offset:-1024
	global_load_dword v202, v[230:231], off offset:-768
	global_load_dword v203, v[230:231], off offset:-512
	global_load_dword v204, v[230:231], off offset:-256
	global_load_dword v205, v[230:231], off offset:0
	v_lshl_add_u64 v[230:231], v[230:231], 0, s[4:5]
	global_load_dword v206, v[230:231], off offset:-1792
	global_load_dword v207, v[230:231], off offset:-1536
	global_load_dword v208, v[230:231], off offset:-1280
	global_load_dword v209, v[230:231], off offset:-1024
	global_load_dword v210, v[230:231], off offset:-768
	global_load_dword v211, v[230:231], off offset:-512
	global_load_dword v212, v[230:231], off offset:-256
	global_load_dword v213, v[230:231], off offset:0
	v_lshl_add_u64 v[230:231], v[230:231], 0, s[4:5]
	global_load_dword v214, v[230:231], off offset:-1792
	global_load_dword v215, v[230:231], off offset:-1536
	global_load_dword v216, v[230:231], off offset:-1280
	global_load_dword v217, v[230:231], off offset:-1024
	global_load_dword v218, v[230:231], off offset:-768
	global_load_dword v219, v[230:231], off offset:-512
	global_load_dword v220, v[230:231], off offset:-256
	global_load_dword v221, v[230:231], off offset:0
	v_lshl_add_u64 v[230:231], v[230:231], 0, s[4:5]
	global_load_dword v222, v[230:231], off offset:-1792
	global_load_dword v223, v[230:231], off offset:-1536
	global_load_dword v224, v[230:231], off offset:-1280
	global_load_dword v225, v[230:231], off offset:-1024
	global_load_dword v226, v[230:231], off offset:-768
	global_load_dword v227, v[230:231], off offset:-512
	global_load_dword v228, v[230:231], off offset:-256
	global_load_dword v229, v[230:231], off offset:0
	s_waitcnt vmcnt(0)
	s_branch .LBB0_57

; __device__ __forceinline__ void p0_h3(const Args& a, int gw, int NGW, int lane) {
;     ...
;         acc = b2;
;         for (int i = 0; i < 64; ++i) acc += __shfl(h, i) * a.in[I_FW2][i * 64 + lane];
;         h = sinf(fr * acc);
.LBB0_82:
	v_readlane_b32 s86, v2, 0
	v_readlane_b32 s87, v2, 1
	v_readlane_b32 s88, v2, 2
	v_readlane_b32 s89, v2, 3
	v_readlane_b32 s90, v2, 4
	v_readlane_b32 s91, v2, 5
	v_readlane_b32 s92, v2, 6
	v_readlane_b32 s93, v2, 7
	v_fmac_f32_e32 v25, s86, v102
	v_fmac_f32_e32 v25, s87, v103
	v_fmac_f32_e32 v25, s88, v104
	v_fmac_f32_e32 v25, s89, v105
	v_fmac_f32_e32 v25, s90, v106
	v_fmac_f32_e32 v25, s91, v107
	v_fmac_f32_e32 v25, s92, v108
	v_fmac_f32_e32 v25, s93, v109
	v_readlane_b32 s86, v2, 8
	v_readlane_b32 s87, v2, 9
	v_readlane_b32 s88, v2, 10
	v_readlane_b32 s89, v2, 11
	v_readlane_b32 s90, v2, 12
	v_readlane_b32 s91, v2, 13
	v_readlane_b32 s92, v2, 14
	v_readlane_b32 s93, v2, 15
	v_fmac_f32_e32 v25, s86, v110
	v_fmac_f32_e32 v25, s87, v111
	v_fmac_f32_e32 v25, s88, v112
	v_fmac_f32_e32 v25, s89, v113
	v_fmac_f32_e32 v25, s90, v114
	v_fmac_f32_e32 v25, s91, v115
	v_fmac_f32_e32 v25, s92, v116
	v_fmac_f32_e32 v25, s93, v117
	v_readlane_b32 s86, v2, 16
	v_readlane_b32 s87, v2, 17
	v_readlane_b32 s88, v2, 18
	v_readlane_b32 s89, v2, 19
	v_readlane_b32 s90, v2, 20
	v_readlane_b32 s91, v2, 21
	v_readlane_b32 s92, v2, 22
	v_readlane_b32 s93, v2, 23
	v_fmac_f32_e32 v25, s86, v118
	v_fmac_f32_e32 v25, s87, v119
	v_fmac_f32_e32 v25, s88, v120
	v_fmac_f32_e32 v25, s89, v121
	v_fmac_f32_e32 v25, s90, v122
	v_fmac_f32_e32 v25, s91, v123
	v_fmac_f32_e32 v25, s92, v124
	v_fmac_f32_e32 v25, s93, v125
	v_readlane_b32 s86, v2, 24
	v_readlane_b32 s87, v2, 25
	v_readlane_b32 s88, v2, 26
	v_readlane_b32 s89, v2, 27
	v_readlane_b32 s90, v2, 28
	v_readlane_b32 s91, v2, 29
	v_readlane_b32 s92, v2, 30
	v_readlane_b32 s93, v2, 31
	v_fmac_f32_e32 v25, s86, v126
	v_fmac_f32_e32 v25, s87, v127
	v_fmac_f32_e32 v25, s88, v128
	v_fmac_f32_e32 v25, s89, v129
	v_fmac_f32_e32 v25, s90, v130
	v_fmac_f32_e32 v25, s91, v131
	v_fmac_f32_e32 v25, s92, v132
	v_fmac_f32_e32 v25, s93, v133
	v_readlane_b32 s86, v2, 32
	v_readlane_b32 s87, v2, 33
	v_readlane_b32 s88, v2, 34
	v_readlane_b32 s89, v2, 35
	v_readlane_b32 s90, v2, 36
	v_readlane_b32 s91, v2, 37
	v_readlane_b32 s92, v2, 38
	v_readlane_b32 s93, v2, 39
	v_fmac_f32_e32 v25, s86, v134
	v_fmac_f32_e32 v25, s87, v135
	v_fmac_f32_e32 v25, s88, v136
	v_fmac_f32_e32 v25, s89, v137
	v_fmac_f32_e32 v25, s90, v138
	v_fmac_f32_e32 v25, s91, v139
	v_fmac_f32_e32 v25, s92, v140
	v_fmac_f32_e32 v25, s93, v141
	v_readlane_b32 s86, v2, 40
	v_readlane_b32 s87, v2, 41
	v_readlane_b32 s88, v2, 42
	v_readlane_b32 s89, v2, 43
	v_readlane_b32 s90, v2, 44
	v_readlane_b32 s91, v2, 45
	v_readlane_b32 s92, v2, 46
	v_readlane_b32 s93, v2, 47
	v_fmac_f32_e32 v25, s86, v142
	v_fmac_f32_e32 v25, s87, v143
	v_fmac_f32_e32 v25, s88, v144
	v_fmac_f32_e32 v25, s89, v145
	v_fmac_f32_e32 v25, s90, v146
	v_fmac_f32_e32 v25, s91, v147
	v_fmac_f32_e32 v25, s92, v148
	v_fmac_f32_e32 v25, s93, v149
	v_readlane_b32 s86, v2, 48
	v_readlane_b32 s87, v2, 49
	v_readlane_b32 s88, v2, 50
	v_readlane_b32 s89, v2, 51
	v_readlane_b32 s90, v2, 52
	v_readlane_b32 s91, v2, 53
	v_readlane_b32 s92, v2, 54
	v_readlane_b32 s93, v2, 55
	v_fmac_f32_e32 v25, s86, v150
	v_fmac_f32_e32 v25, s87, v151
	v_fmac_f32_e32 v25, s88, v152
	v_fmac_f32_e32 v25, s89, v153
	v_fmac_f32_e32 v25, s90, v154
	v_fmac_f32_e32 v25, s91, v155
	v_fmac_f32_e32 v25, s92, v156
	v_fmac_f32_e32 v25, s93, v157
	v_readlane_b32 s86, v2, 56
	v_readlane_b32 s87, v2, 57
	v_readlane_b32 s88, v2, 58
	v_readlane_b32 s89, v2, 59
	v_readlane_b32 s90, v2, 60
	v_readlane_b32 s91, v2, 61
	v_readlane_b32 s92, v2, 62
	v_readlane_b32 s93, v2, 63
	v_fmac_f32_e32 v25, s86, v158
	v_fmac_f32_e32 v25, s87, v159
	v_fmac_f32_e32 v25, s88, v160
	v_fmac_f32_e32 v25, s89, v161
	v_fmac_f32_e32 v25, s90, v162
	v_fmac_f32_e32 v25, s91, v163
	v_fmac_f32_e32 v25, s92, v164
	v_fmac_f32_e32 v25, s93, v165
	v_mul_f32_e32 v12, v1, v25
	v_and_b32_e32 v13, 0x7fffffff, v12
	v_cmp_nlt_f32_e64 s[2:3], |v12|, s27
	s_and_saveexec_b64 s[12:13], s[2:3]
	s_xor_b64 s[2:3], exec, s[12:13]
	s_cbranch_execz .LBB0_85
	v_lshrrev_b32_e32 v2, 23, v13
	v_add_u32_e32 v2, 0xffffff88, v2
	v_cmp_lt_u32_e32 vcc, 63, v2
	s_nop 1
	v_cndmask_b32_e32 v25, 0, v21, vcc
	v_add_u32_e32 v2, v25, v2
	v_cmp_lt_u32_e64 s[12:13], 31, v2
	s_nop 1
	v_cndmask_b32_e64 v25, 0, v22, s[12:13]
	v_add_u32_e32 v2, v25, v2
	v_cmp_lt_u32_e64 s[14:15], 31, v2
	s_nop 1
	v_cndmask_b32_e64 v25, 0, v22, s[14:15]
	v_add_u32_e32 v25, v25, v2
	v_and_b32_e32 v2, 0x7fffff, v13
	v_or_b32_e32 v38, 0x800000, v2
	v_mad_u64_u32 v[26:27], s[16:17], v38, s28, 0
	v_mov_b32_e32 v2, v27
	v_mad_u64_u32 v[28:29], s[16:17], v38, s29, v[2:3]
	v_mov_b32_e32 v2, v29
	v_mad_u64_u32 v[30:31], s[16:17], v38, s30, v[2:3]
	v_mov_b32_e32 v2, v31
	v_mad_u64_u32 v[32:33], s[16:17], v38, s31, v[2:3]
	v_mov_b32_e32 v2, v33
	v_mad_u64_u32 v[34:35], s[16:17], v38, s33, v[2:3]
	v_mov_b32_e32 v2, v35
	v_mad_u64_u32 v[36:37], s[16:17], v38, s34, v[2:3]
	v_mov_b32_e32 v2, v37
	v_mad_u64_u32 v[38:39], s[16:17], v38, s35, v[2:3]
	v_cndmask_b32_e32 v27, v36, v32, vcc
	v_cndmask_b32_e32 v2, v38, v34, vcc
	v_cndmask_b32_e32 v31, v39, v36, vcc
	v_cndmask_b32_e64 v29, v2, v27, s[12:13]
	v_cndmask_b32_e64 v2, v31, v2, s[12:13]
	v_cndmask_b32_e32 v31, v34, v30, vcc
	v_cndmask_b32_e64 v27, v27, v31, s[12:13]
	v_sub_u32_e32 v33, 32, v25
	v_cmp_eq_u32_e64 s[16:17], 0, v25
	v_cndmask_b32_e32 v25, v32, v28, vcc
	v_cndmask_b32_e64 v2, v2, v29, s[14:15]
	v_cndmask_b32_e64 v29, v29, v27, s[14:15]
	v_cndmask_b32_e64 v28, v31, v25, s[12:13]
	v_alignbit_b32 v34, v2, v29, v33
	v_cndmask_b32_e64 v27, v27, v28, s[14:15]
	v_cndmask_b32_e64 v2, v34, v2, s[16:17]
	v_alignbit_b32 v31, v29, v27, v33
	v_cndmask_b32_e32 v26, v30, v26, vcc
	v_cndmask_b32_e64 v29, v31, v29, s[16:17]
	v_bfe_u32 v34, v2, 29, 1
	v_cndmask_b32_e64 v25, v25, v26, s[12:13]
	v_alignbit_b32 v31, v2, v29, 30
	v_sub_u32_e32 v35, 0, v34
	v_cndmask_b32_e64 v25, v28, v25, s[14:15]
	v_xor_b32_e32 v31, v31, v35
	v_alignbit_b32 v26, v27, v25, v33
	v_cndmask_b32_e64 v26, v26, v27, s[16:17]
	v_ffbh_u32_e32 v28, v31
	v_alignbit_b32 v27, v29, v26, 30
	v_min_u32_e32 v28, 32, v28
	v_alignbit_b32 v25, v26, v25, 30
	v_xor_b32_e32 v27, v27, v35
	v_sub_u32_e32 v29, 31, v28
	v_xor_b32_e32 v25, v25, v35
	v_alignbit_b32 v30, v31, v27, v29
	v_alignbit_b32 v25, v27, v25, v29
	v_alignbit_b32 v26, v30, v25, 9
	v_ffbh_u32_e32 v27, v26
	v_min_u32_e32 v27, 32, v27
	v_lshrrev_b32_e32 v32, 29, v2
	v_not_b32_e32 v29, v27
	v_alignbit_b32 v25, v26, v25, v29
	v_lshlrev_b32_e32 v26, 31, v32
	v_or_b32_e32 v29, 0x33000000, v26
	v_add_lshl_u32 v27, v27, v28, 23
	v_lshrrev_b32_e32 v25, 9, v25
	v_sub_u32_e32 v27, v29, v27
	v_or_b32_e32 v26, 0.5, v26
	v_lshlrev_b32_e32 v28, 23, v28
	v_or_b32_e32 v25, v27, v25
	v_lshrrev_b32_e32 v27, 9, v30
	v_sub_u32_e32 v26, v26, v28
	v_or_b32_e32 v26, v27, v26
	v_mul_f32_e32 v27, 0x3fc90fda, v26
	v_fma_f32 v28, v26, s36, -v27
	v_fmac_f32_e32 v28, 0x33a22168, v26
	v_fmac_f32_e32 v28, 0x3fc90fda, v25
	v_lshrrev_b32_e32 v2, 30, v2
	v_add_f32_e32 v25, v27, v28
	v_add_u32_e32 v2, v34, v2

; __device__ __forceinline__ void p0_h3(const Args& a, int gw, int NGW, int lane) {
;     ...
;         acc = b3;
;         for (int i = 0; i < 64; ++i) acc += __shfl(h, i) * a.in[I_FW3][i * 64 + lane];
;         h = sinf(fr * acc);
.LBB0_88:
	v_readlane_b32 s86, v2, 0
	v_readlane_b32 s87, v2, 1
	v_readlane_b32 s88, v2, 2
	v_readlane_b32 s89, v2, 3
	v_readlane_b32 s90, v2, 4
	v_readlane_b32 s91, v2, 5
	v_readlane_b32 s92, v2, 6
	v_readlane_b32 s93, v2, 7
	v_fmac_f32_e32 v25, s86, v166
	v_fmac_f32_e32 v25, s87, v167
	v_fmac_f32_e32 v25, s88, v168
	v_fmac_f32_e32 v25, s89, v169
	v_fmac_f32_e32 v25, s90, v170
	v_fmac_f32_e32 v25, s91, v171
	v_fmac_f32_e32 v25, s92, v172
	v_fmac_f32_e32 v25, s93, v173
	v_readlane_b32 s86, v2, 8
	v_readlane_b32 s87, v2, 9
	v_readlane_b32 s88, v2, 10
	v_readlane_b32 s89, v2, 11
	v_readlane_b32 s90, v2, 12
	v_readlane_b32 s91, v2, 13
	v_readlane_b32 s92, v2, 14
	v_readlane_b32 s93, v2, 15
	v_fmac_f32_e32 v25, s86, v174
	v_fmac_f32_e32 v25, s87, v175
	v_fmac_f32_e32 v25, s88, v176
	v_fmac_f32_e32 v25, s89, v177
	v_fmac_f32_e32 v25, s90, v178
	v_fmac_f32_e32 v25, s91, v179
	v_fmac_f32_e32 v25, s92, v180
	v_fmac_f32_e32 v25, s93, v181
	v_readlane_b32 s86, v2, 16
	v_readlane_b32 s87, v2, 17
	v_readlane_b32 s88, v2, 18
	v_readlane_b32 s89, v2, 19
	v_readlane_b32 s90, v2, 20
	v_readlane_b32 s91, v2, 21
	v_readlane_b32 s92, v2, 22
	v_readlane_b32 s93, v2, 23
	v_fmac_f32_e32 v25, s86, v182
	v_fmac_f32_e32 v25, s87, v183
	v_fmac_f32_e32 v25, s88, v184
	v_fmac_f32_e32 v25, s89, v185
	v_fmac_f32_e32 v25, s90, v186
	v_fmac_f32_e32 v25, s91, v187
	v_fmac_f32_e32 v25, s92, v188
	v_fmac_f32_e32 v25, s93, v189
	v_readlane_b32 s86, v2, 24
	v_readlane_b32 s87, v2, 25
	v_readlane_b32 s88, v2, 26
	v_readlane_b32 s89, v2, 27
	v_readlane_b32 s90, v2, 28
	v_readlane_b32 s91, v2, 29
	v_readlane_b32 s92, v2, 30
	v_readlane_b32 s93, v2, 31
	v_fmac_f32_e32 v25, s86, v190
	v_fmac_f32_e32 v25, s87, v191
	v_fmac_f32_e32 v25, s88, v192
	v_fmac_f32_e32 v25, s89, v193
	v_fmac_f32_e32 v25, s90, v194
	v_fmac_f32_e32 v25, s91, v195
	v_fmac_f32_e32 v25, s92, v196
	v_fmac_f32_e32 v25, s93, v197
	v_readlane_b32 s86, v2, 32
	v_readlane_b32 s87, v2, 33
	v_readlane_b32 s88, v2, 34
	v_readlane_b32 s89, v2, 35
	v_readlane_b32 s90, v2, 36
	v_readlane_b32 s91, v2, 37
	v_readlane_b32 s92, v2, 38
	v_readlane_b32 s93, v2, 39
	v_fmac_f32_e32 v25, s86, v198
	v_fmac_f32_e32 v25, s87, v199
	v_fmac_f32_e32 v25, s88, v200
	v_fmac_f32_e32 v25, s89, v201
	v_fmac_f32_e32 v25, s90, v202
	v_fmac_f32_e32 v25, s91, v203
	v_fmac_f32_e32 v25, s92, v204
	v_fmac_f32_e32 v25, s93, v205
	v_readlane_b32 s86, v2, 40
	v_readlane_b32 s87, v2, 41
	v_readlane_b32 s88, v2, 42
	v_readlane_b32 s89, v2, 43
	v_readlane_b32 s90, v2, 44
	v_readlane_b32 s91, v2, 45
	v_readlane_b32 s92, v2, 46
	v_readlane_b32 s93, v2, 47
	v_fmac_f32_e32 v25, s86, v206
	v_fmac_f32_e32 v25, s87, v207
	v_fmac_f32_e32 v25, s88, v208
	v_fmac_f32_e32 v25, s89, v209
	v_fmac_f32_e32 v25, s90, v210
	v_fmac_f32_e32 v25, s91, v211
	v_fmac_f32_e32 v25, s92, v212
	v_fmac_f32_e32 v25, s93, v213
	v_readlane_b32 s86, v2, 48
	v_readlane_b32 s87, v2, 49
	v_readlane_b32 s88, v2, 50
	v_readlane_b32 s89, v2, 51
	v_readlane_b32 s90, v2, 52
	v_readlane_b32 s91, v2, 53
	v_readlane_b32 s92, v2, 54
	v_readlane_b32 s93, v2, 55
	v_fmac_f32_e32 v25, s86, v214
	v_fmac_f32_e32 v25, s87, v215
	v_fmac_f32_e32 v25, s88, v216
	v_fmac_f32_e32 v25, s89, v217
	v_fmac_f32_e32 v25, s90, v218
	v_fmac_f32_e32 v25, s91, v219
	v_fmac_f32_e32 v25, s92, v220
	v_fmac_f32_e32 v25, s93, v221
	v_readlane_b32 s86, v2, 56
	v_readlane_b32 s87, v2, 57
	v_readlane_b32 s88, v2, 58
	v_readlane_b32 s89, v2, 59
	v_readlane_b32 s90, v2, 60
	v_readlane_b32 s91, v2, 61
	v_readlane_b32 s92, v2, 62
	v_readlane_b32 s93, v2, 63
	v_fmac_f32_e32 v25, s86, v222
	v_fmac_f32_e32 v25, s87, v223
	v_fmac_f32_e32 v25, s88, v224
	v_fmac_f32_e32 v25, s89, v225
	v_fmac_f32_e32 v25, s90, v226
	v_fmac_f32_e32 v25, s91, v227
	v_fmac_f32_e32 v25, s92, v228
	v_fmac_f32_e32 v25, s93, v229
	v_mul_f32_e32 v12, v1, v25
	v_and_b32_e32 v13, 0x7fffffff, v12
	v_cmp_nlt_f32_e64 s[2:3], |v12|, s27
	s_and_saveexec_b64 s[12:13], s[2:3]
	s_xor_b64 s[2:3], exec, s[12:13]
	s_cbranch_execz .LBB0_91
	v_lshrrev_b32_e32 v2, 23, v13
	v_add_u32_e32 v2, 0xffffff88, v2
	v_cmp_lt_u32_e32 vcc, 63, v2
	s_nop 1
	v_cndmask_b32_e32 v25, 0, v21, vcc
	v_add_u32_e32 v2, v25, v2
	v_cmp_lt_u32_e64 s[12:13], 31, v2
	s_nop 1
	v_cndmask_b32_e64 v25, 0, v22, s[12:13]
	v_add_u32_e32 v2, v25, v2
	v_cmp_lt_u32_e64 s[14:15], 31, v2
	s_nop 1
	v_cndmask_b32_e64 v25, 0, v22, s[14:15]
	v_add_u32_e32 v25, v25, v2
	v_and_b32_e32 v2, 0x7fffff, v13
	v_or_b32_e32 v38, 0x800000, v2
	v_mad_u64_u32 v[26:27], s[16:17], v38, s28, 0
	v_mov_b32_e32 v2, v27
	v_mad_u64_u32 v[28:29], s[16:17], v38, s29, v[2:3]
	v_mov_b32_e32 v2, v29
	v_mad_u64_u32 v[30:31], s[16:17], v38, s30, v[2:3]
	v_mov_b32_e32 v2, v31
	v_mad_u64_u32 v[32:33], s[16:17], v38, s31, v[2:3]
	v_mov_b32_e32 v2, v33
	v_mad_u64_u32 v[34:35], s[16:17], v38, s33, v[2:3]
	v_mov_b32_e32 v2, v35
	v_mad_u64_u32 v[36:37], s[16:17], v38, s34, v[2:3]
	v_mov_b32_e32 v2, v37
	v_mad_u64_u32 v[38:39], s[16:17], v38, s35, v[2:3]
	v_cndmask_b32_e32 v27, v36, v32, vcc
	v_cndmask_b32_e32 v2, v38, v34, vcc
	v_cndmask_b32_e32 v31, v39, v36, vcc
	v_cndmask_b32_e64 v29, v2, v27, s[12:13]
	v_cndmask_b32_e64 v2, v31, v2, s[12:13]
	v_cndmask_b32_e32 v31, v34, v30, vcc
	v_cndmask_b32_e64 v27, v27, v31, s[12:13]
	v_sub_u32_e32 v33, 32, v25
	v_cmp_eq_u32_e64 s[16:17], 0, v25
	v_cndmask_b32_e32 v25, v32, v28, vcc
	v_cndmask_b32_e64 v2, v2, v29, s[14:15]
	v_cndmask_b32_e64 v29, v29, v27, s[14:15]
	v_cndmask_b32_e64 v28, v31, v25, s[12:13]
	v_alignbit_b32 v34, v2, v29, v33
	v_cndmask_b32_e64 v27, v27, v28, s[14:15]
	v_cndmask_b32_e64 v2, v34, v2, s[16:17]
	v_alignbit_b32 v31, v29, v27, v33
	v_cndmask_b32_e32 v26, v30, v26, vcc
	v_cndmask_b32_e64 v29, v31, v29, s[16:17]
	v_bfe_u32 v34, v2, 29, 1
	v_cndmask_b32_e64 v25, v25, v26, s[12:13]
	v_alignbit_b32 v31, v2, v29, 30
	v_sub_u32_e32 v35, 0, v34
	v_cndmask_b32_e64 v25, v28, v25, s[14:15]
	v_xor_b32_e32 v31, v31, v35
	v_alignbit_b32 v26, v27, v25, v33
	v_cndmask_b32_e64 v26, v26, v27, s[16:17]
	v_ffbh_u32_e32 v28, v31
	v_alignbit_b32 v27, v29, v26, 30
	v_min_u32_e32 v28, 32, v28
	v_alignbit_b32 v25, v26, v25, 30
	v_xor_b32_e32 v27, v27, v35
	v_sub_u32_e32 v29, 31, v28
	v_xor_b32_e32 v25, v25, v35
	v_alignbit_b32 v30, v31, v27, v29
	v_alignbit_b32 v25, v27, v25, v29
	v_alignbit_b32 v26, v30, v25, 9
	v_ffbh_u32_e32 v27, v26
	v_min_u32_e32 v27, 32, v27
	v_lshrrev_b32_e32 v32, 29, v2
	v_not_b32_e32 v29, v27
	v_alignbit_b32 v25, v26, v25, v29
	v_lshlrev_b32_e32 v26, 31, v32
	v_or_b32_e32 v29, 0x33000000, v26
	v_add_lshl_u32 v27, v27, v28, 23
	v_lshrrev_b32_e32 v25, 9, v25
	v_sub_u32_e32 v27, v29, v27
	v_or_b32_e32 v26, 0.5, v26
	v_lshlrev_b32_e32 v28, 23, v28
	v_or_b32_e32 v25, v27, v25
	v_lshrrev_b32_e32 v27, 9, v30
	v_sub_u32_e32 v26, v26, v28
	v_or_b32_e32 v26, v27, v26
	v_mul_f32_e32 v27, 0x3fc90fda, v26
	v_fma_f32 v28, v26, s36, -v27
	v_fmac_f32_e32 v28, 0x33a22168, v26
	v_fmac_f32_e32 v28, 0x3fc90fda, v25
	v_lshrrev_b32_e32 v2, 30, v2
	v_add_f32_e32 v25, v27, v28
	v_add_u32_e32 v2, v34, v2
